# scan loader waves sleep ~400 cycles after the chunk barrier before their LDS write burst (staggered against the scan waves' chunk start)
# speedup vs baseline: 1.0036x; 1.0036x over previous
; #define LAS __attribute__((address_space(3)))
; __device__ __forceinline__ void scan_load_chunk(LAS unsigned char* slot, const float* Wd, const float* V, const bf16_t* RKKB, int p, int rg, int s0, int lt) {
;     ...
;     for (int j = 0; j < 2; ++j) { const int idx = lt + 256 * j, st = idx >> 4, part = idx & 15; *(LAS u32x4*)(slot + st * SCAN_STEP_B + part * 16) = r[j]; }
; #pragma unroll
;     for (int j = 2; j < 6; ++j) { const int k = lt + 256 * (j - 2), st = k >> 5, rem = k & 31, q = rem >> 3, part = rem & 7; const u32x4 w = r[j];
;         const int Q = (q == 0) ? 4 : (q == 1) ? 2 : (q == 2) ? 3 : 1;
;         LAS f32x4* d = (LAS f32x4*)(slot + st * SCAN_STEP_B + Q * 256 + part * 32);
.LBB0_348:
	s_andn2_b64 vcc, exec, s[18:19]
	s_cbranch_vccnz .LBB0_345
	s_cmpk_gt_u32 s22, 0x7d
	s_cbranch_scc1 .LBB0_344
	s_sleep 6
	s_nop 0
	s_add_i32 s18, s22, 2
	s_mul_i32 s19, s18, 0xab
	s_bfe_u32 s19, s19, 0x70009
	s_mul_i32 s19, s19, 3
	s_sub_i32 s18, s18, s19
	s_and_b32 s18, s18, 0xff
	s_mul_i32 s18, s18, 0xa800
	s_add_i32 s23, s18, 0
	v_add_u32_e32 v0, s23, v73
	v_add_u32_e32 v34, v0, v74
	v_add_u32_e32 v0, v0, v75
	s_waitcnt vmcnt(0)
	ds_write_b128 v34, v[130:133]
	ds_write_b128 v0, v[126:129]
	v_cmp_lt_i32_e32 vcc, 0, v69
	v_mov_b32_e32 v0, 0x400
	s_and_saveexec_b64 s[18:19], vcc
	s_cbranch_execz .LBB0_356
	v_cmp_ne_u32_e32 vcc, 1, v69
	s_and_saveexec_b64 s[20:21], vcc
	s_xor_b64 s[20:21], exec, s[20:21]
	s_or_saveexec_b64 s[20:21], s[20:21]
	v_mov_b32_e32 v0, v70
	s_xor_b64 exec, exec, s[20:21]
	v_mov_b32_e32 v0, 0x200
	s_or_b64 exec, exec, s[20:21]
